# speedup vs baseline: 1.0193x; 1.0061x over previous
; __global__ void __launch_bounds__(NT, 2) k_mega(Params p) {
;     ...
;   cg::grid_group grid = cg::this_grid();
;     ...
;   run_phase(p, PH_PREP, 0, 0, smem);
;   grid.sync();
;   constexpr int NSTEP = 10 * DEPTH;
; #pragma unroll 1
;   for (int s = 0; s < NSTEP; ++s) {
;     const int l = s / 10, q = s - l * 10;
;     const int ph = PH_INPROJ + q, c = 0;
;     run_phase(p, ph, l, c, smem);
;     if (s + 1 < NSTEP) xcd_barrier(xb, (unsigned)s);
.LBB0_142:
	s_or_b64 exec, exec, s[4:5]
	v_lshrrev_b32_e32 v1, 20, v0
	v_lshrrev_b32_e32 v0, 10, v0
	v_or_b32_e32 v0, v0, v1
	s_movk_i32 s0, 0x3ff
	v_and_or_b32 v0, v0, s0, v160
	v_cmp_eq_u32_e32 vcc, 0, v0
	s_barrier
	s_and_saveexec_b64 s[0:1], vcc
	s_branch .LBB0_152
.LBB0_152:
	v_writelane_b32 v253, s44, 44
	s_nop 1
	v_writelane_b32 v253, s45, 45
	s_or_b64 exec, exec, s[0:1]
	v_readlane_b32 s36, v253, 6
	s_lshl_b32 s66, s33, 3
	v_readlane_b32 s46, v253, 16
	v_readlane_b32 s47, v253, 17
	s_cmp_lg_u64 s[46:47], 0
	s_cselect_b64 s[0:1], -1, 0
	v_readlane_b32 s37, v253, 7
	v_readlane_b32 s38, v253, 8
	v_readlane_b32 s39, v253, 9
	v_readlane_b32 s40, v253, 10
	v_readlane_b32 s41, v253, 11
	v_readlane_b32 s42, v253, 12
	v_readlane_b32 s43, v253, 13
	v_readlane_b32 s44, v253, 14
	v_readlane_b32 s45, v253, 15
	v_readlane_b32 s48, v253, 18
	v_readlane_b32 s49, v253, 19
	v_readlane_b32 s50, v253, 20
	v_readlane_b32 s51, v253, 21
	v_writelane_b32 v253, s0, 46
	s_mov_b32 s19, 0
	v_mov_b32_e32 v129, 0
	v_writelane_b32 v253, s1, 47
	v_mov_b32_e32 v162, 0x358637bd
	v_readlane_b32 s84, v253, 22
	v_readlane_b32 s85, v253, 23
	s_add_u32 s0, s84, 0x2000
	s_addc_u32 s1, s85, 0
	v_readlane_b32 s86, v253, 24
	v_readlane_b32 s87, v253, 25
	v_readlane_b32 s88, v253, 26
	v_readlane_b32 s89, v253, 27
	v_readlane_b32 s90, v253, 28
	v_readlane_b32 s91, v253, 29
	v_readlane_b32 s92, v253, 30
	v_readlane_b32 s93, v253, 31
	v_readlane_b32 s94, v253, 32
	v_readlane_b32 s95, v253, 33
	v_readlane_b32 s96, v253, 34
	v_readlane_b32 s97, v253, 35
	v_readlane_b32 s98, v253, 36
	v_readlane_b32 s99, v253, 37
	v_writelane_b32 v253, s0, 48
	s_movk_i32 s99, 0x400
	v_mov_b32_e32 v163, 0xc0135761
	v_writelane_b32 v253, s1, 49
	s_add_u32 s0, s92, 0x2c00000
	s_addc_u32 s1, s93, 0
	v_writelane_b32 v253, s0, 50
	v_mov_b32_e32 v164, 0x3ecc95a3
	v_mov_b32_e32 v165, 0x3727c5ac
	v_writelane_b32 v253, s1, 51
	s_add_u32 s0, s86, 0x5800000
	s_addc_u32 s1, s87, 0
	v_writelane_b32 v253, s0, 52
	v_mov_b32_e32 v166, 1
	v_mov_b32_e32 v167, 0x42800000
	v_writelane_b32 v253, s1, 53
	s_add_u32 s0, s38, 0x2800000
	s_addc_u32 s1, s39, 0
	v_writelane_b32 v253, s0, 54
	s_lshl_b32 s3, s33, 9
	v_mov_b32_e32 v168, 0x7fc00000
	v_writelane_b32 v253, s1, 55
	s_lshl_b32 s0, s2, 9
	s_cmp_lg_u64 s[50:51], 0
	v_writelane_b32 v253, s0, 56
	s_cselect_b64 s[0:1], -1, 0
	v_writelane_b32 v253, s0, 57
	v_mov_b32_e32 v169, 0xff800000
	v_not_b32_e32 v170, 63
	v_writelane_b32 v253, s1, 58
	s_add_u32 s0, s50, 0x2000
	s_addc_u32 s1, s51, 0
	v_writelane_b32 v253, s0, 59
	v_mov_b32_e32 v171, 0x41b17218
	v_mov_b32_e32 v172, 0x16000
	v_writelane_b32 v253, s1, 60
	s_add_u32 s0, s48, 0x2000
	s_addc_u32 s1, s49, 0
	v_writelane_b32 v253, s0, 61
	s_cmpk_lt_i32 s2, 0x400
	v_mov_b32_e32 v173, 0x5000000
	v_writelane_b32 v253, s1, 62
	s_cselect_b64 s[0:1], -1, 0
	v_writelane_b32 v253, s0, 63
	s_cmpk_lt_i32 s2, 0x800
	v_mov_b32_e32 v130, 0x3db504f3
	v_writelane_b32 v252, s1, 0
	s_cselect_b64 s[0:1], -1, 0
	v_writelane_b32 v252, s0, 1
	s_lshl_b32 s4, s18, 6
	s_add_i32 s18, s4, 0x500
	v_writelane_b32 v252, s1, 2
	s_and_b32 s0, s2, 7
	s_lshr_b32 s1, s33, 3
	s_mul_i32 s0, s1, s0
	s_lshr_b32 s1, s2, 3
	s_add_i32 s5, s0, s1
	s_lshl_b64 s[0:1], s[18:19], 2
	s_add_u32 s0, s64, s0
	s_addc_u32 s1, s65, s1
	v_writelane_b32 v252, s0, 3
	s_add_i32 s18, s4, 0x900
	v_mov_b32_e32 v174, 0xf149f2ca
	v_writelane_b32 v252, s1, 4
	s_lshl_b64 s[0:1], s[18:19], 2
	s_add_u32 s0, s64, s0
	s_addc_u32 s1, s65, s1
	v_writelane_b32 v252, s0, 5
	v_mov_b32_e32 v175, 0x7f
	v_mov_b32_e32 v176, 0x2c00
	v_writelane_b32 v252, s1, 6
	s_add_u32 s0, s64, 0x200
	s_addc_u32 s1, s65, 0
	v_writelane_b32 v252, s0, 7
	v_mov_b32_e32 v177, 0x105f0
	v_mov_b32_e32 v178, 0x5800
	v_writelane_b32 v252, s1, 8
	s_add_u32 s0, s64, 0x3400
	s_addc_u32 s1, s65, 0
	v_writelane_b32 v252, s0, 9
	v_mov_b32_e32 v179, 0x106f8
	s_mov_b32 s60, 0x8000
	v_writelane_b32 v252, s1, 10
	s_add_u32 s0, s64, 0x3500
	s_addc_u32 s1, s65, 0
	v_writelane_b32 v252, s0, 11
	s_mov_b32 s64, s3
	s_mov_b32 s65, s5
	v_writelane_b32 v252, s1, 12
	s_add_u32 s0, s46, 0x2000
	s_addc_u32 s1, s47, 0
	v_writelane_b32 v252, s0, 13
	s_movk_i32 s61, 0x1000
	s_mov_b32 s84, 0x800000
	v_writelane_b32 v252, s1, 14
	s_add_u32 s0, s40, 0x1000000
	s_addc_u32 s1, s41, 0
	v_writelane_b32 v252, s0, 15
	s_ashr_i32 s67, s66, 31
	s_movk_i32 s98, 0x80
	v_writelane_b32 v252, s1, 16
	s_lshl_b64 s[0:1], s[66:67], 12
	v_writelane_b32 v252, s0, 17
	s_movk_i32 s85, 0x2c00
	s_movk_i32 s88, 0x2800
	v_writelane_b32 v252, s1, 18
	v_readlane_b32 s0, v253, 42
	s_add_i32 s0, s0, s66
	s_movk_i32 s89, 0x110
	v_writelane_b32 v252, s0, 19
	s_add_u32 s0, s94, 0x1000
	s_addc_u32 s1, s95, 0
	v_writelane_b32 v252, s0, 20
	s_movk_i32 s30, 0x90
	s_mov_b32 s31, 0xbfb8aa3b
	v_writelane_b32 v252, s1, 21
	s_lshl_b64 s[0:1], s[66:67], 13
	v_writelane_b32 v252, s0, 22
	s_lshl_b32 s67, s33, 8
	s_mov_b32 s29, 0x3f317217
	v_writelane_b32 v252, s1, 23
	s_lshl_b32 s0, s2, 8
	v_writelane_b32 v252, s0, 24
	s_lshl_b32 s0, s2, 2
	v_writelane_b32 v252, s0, 25
	s_lshl_b32 s0, s33, 2
	v_writelane_b32 v252, s0, 26
	s_lshl_b32 s0, s2, 12
	v_writelane_b32 v252, s0, 27
	s_add_u32 s0, s36, 0x1000
	s_addc_u32 s1, s37, 0
	v_writelane_b32 v252, s0, 28
	s_mov_b32 s36, 0x7f800000
	s_mov_b32 s37, 0xc2dc0000
	v_writelane_b32 v252, s1, 29
	v_readlane_b32 s0, v253, 0
	v_readlane_b32 s2, v253, 2
	v_readlane_b32 s3, v253, 3
	s_add_u32 s4, s2, 8
	v_writelane_b32 v252, s4, 30
	s_addc_u32 s0, s3, 0
	v_readlane_b32 s1, v253, 1
	v_writelane_b32 v252, s0, 31
	s_mov_b32 s0, s66
	v_writelane_b32 v252, s0, 32
	s_mov_b32 s38, 0xf149f2ca
	s_mov_b32 s39, 0xefa18f08
	v_writelane_b32 v252, s1, 33
	v_writelane_b32 v252, s64, 34
	s_movk_i32 s40, 0x1ff
	s_mov_b32 s12, 0
	s_mov_b64 s[90:91], 0x1800
	s_mov_b64 s[86:87], 0xa0000
	s_mov_b64 s[8:9], 0x80
	s_mov_b64 s[96:97], 0x1600
	v_writelane_b32 v252, s65, 35
	s_barrier
	v_writelane_b32 v252, s67, 36
	s_mov_b32 s0, -1
	v_writelane_b32 v252, s0, 37
	s_mov_b32 s0, 0
	v_writelane_b32 v252, s0, 44
	s_branch .LBB0_818

; __global__ void __launch_bounds__(NT, 2) k_mega(Params p) {
;     ...
;   for (int s = 0; s < NSTEP; ++s) {
;     const int l = s / 10, q = s - l * 10;
;     const int ph = PH_INPROJ + q, c = 0;
;     run_phase(p, ph, l, c, smem);
;     if (s + 1 < NSTEP) xcd_barrier(xb, (unsigned)s);
;   }
.LBB0_154:
	s_or_b64 exec, exec, s[0:1]
	s_barrier
	v_readlane_b32 s12, v252, 37
	s_add_i32 s12, s12, 1

; DEV unsigned xb_ld(unsigned* p) { return __hip_atomic_load(p, __ATOMIC_RELAXED, __HIP_MEMORY_SCOPE_AGENT); }
; DEV unsigned xb_add(unsigned* p, unsigned v) { return __hip_atomic_fetch_add(p, v, __ATOMIC_RELAXED, __HIP_MEMORY_SCOPE_AGENT); }
; #define XB_SPIN(cond, bar) do { unsigned _sp = 0; while (cond) { __builtin_amdgcn_s_sleep(1); \
;     if ((++_sp & 255u) == 0u) { if (xb_ld(&(bar)[XB_TMO])) break; if (_sp > XB_SPIN_CAP) { atomicAdd(&(bar)[XB_TMO], 1u); break; } } } } while (0)
; DEV void xcd_barrier(const XcdBarrier& b, unsigned k) {
;   asm volatile("s_waitcnt vmcnt(0)" ::: "memory");
;   __syncthreads();
;   if (threadIdx.x == 0) {
;     unsigned* bar = b.bar;
;     __builtin_amdgcn_s_waitcnt(0);
;     const unsigned old = xb_add(&bar[XB_XSUB(b.x)], 1u);
;     const unsigned gen = k;
;     if (old + 1u == (gen + 1u) * b.nloc) {
;       __builtin_amdgcn_fence(__ATOMIC_RELEASE, "agent");
;       asm volatile("s_waitcnt vmcnt(0)" ::: "memory");
;       const unsigned og = xb_add(&bar[XB_TOP], 1u);
;       const unsigned tg = k;
;       if (og + 1u == (tg + 1u) * b.nx) xb_add(&bar[XB_TOPGEN], 1u);
;       else XB_SPIN(xb_ld(&bar[XB_TOPGEN]) == tg, bar);
;       __builtin_amdgcn_fence(__ATOMIC_ACQUIRE, "agent");
;       xb_add(&bar[XB_XGEN(b.x)], 1u);
;     } else {
;       XB_SPIN(xb_ld(&bar[XB_XGEN(b.x)]) == gen, bar);
;       __builtin_amdgcn_fence(__ATOMIC_ACQUIRE, "agent");
;     }
;   }
;   __syncthreads();
; }
; __global__ void __launch_bounds__(NT, 2) k_mega(Params p) {
;     ...
;     if (s + 1 < NSTEP) xcd_barrier(xb, (unsigned)s);
.LBB0_818:
	v_readlane_b32 s14, v252, 37
	s_add_i32 s12, s14, 1
	s_cmp_eq_u32 s14, 19
	s_cbranch_scc1 .LBB0_155
	v_readlane_b32 s14, v252, 44
	s_add_i32 s12, s14, 1
	v_writelane_b32 v252, s12, 44
	s_waitcnt vmcnt(0)
	s_waitcnt vmcnt(0) lgkmcnt(0)
	s_barrier
	s_mov_b64 s[0:1], exec
	v_readlane_b32 s2, v253, 4
	v_readlane_b32 s3, v253, 5
	s_and_b64 s[2:3], s[0:1], s[2:3]
	s_mov_b64 exec, s[2:3]
	s_cbranch_execz .LBB0_154
	s_mov_b64 s[2:3], exec
	v_mbcnt_lo_u32_b32 v0, s2, 0
	v_mbcnt_hi_u32_b32 v0, s3, v0
	v_cmp_eq_u32_e32 vcc, 0, v0
	s_waitcnt vmcnt(0) expcnt(0) lgkmcnt(0)
	s_and_saveexec_b64 s[4:5], vcc
	s_cbranch_execz .LBB0_822
	s_bcnt1_i32_b64 s2, s[2:3]
	v_mov_b32_e32 v1, s2
	v_readlane_b32 s2, v252, 3
	v_readlane_b32 s3, v252, 4
	s_nop 4
	global_atomic_add v1, v129, v1, s[2:3] sc0
